# phase-1 GEMM tile rewritten by hand: LDS-DMA triple-buffered activation tile, one barrier per K step, weights prefetched 1.5 steps ahead
# speedup vs baseline: 1.1562x; 1.0011x over previous
.LBB0_161:
	v_and_b32_e32 v246, 63, v208
	v_lshrrev_b32_e32 v247, 6, v208
	v_lshrrev_b32_e32 v248, 3, v246
	v_and_b32_e32 v249, 7, v246
	v_xor_b32_e32 v249, v249, v248
	v_lshlrev_b32_e32 v249, 4, v249
	v_lshl_add_u32 v250, v247, 5, v248
	v_lshl_add_u32 v234, v250, 11, v249
	v_add_u32_e32 v235, 0x4000, v234
	v_add_u32_e32 v236, 0x8000, v234
	v_add_u32_e32 v237, 0xc000, v234
	s_lshl_b32 s0, s24, 18
	s_add_u32 s28, s92, s0
	s_addc_u32 s29, s93, 0
	v_lshlrev_b32_e32 v238, 4, v246
	v_add_u32_e32 v239, 0x8000, v238
	v_add_u32_e32 v240, 0x10000, v238
	v_add_u32_e32 v241, 0x18000, v238
	v_readfirstlane_b32 s0, v247
	s_lshl_b32 s97, s0, 12
	s_lshl_b32 s0, s0, 17
	s_lshl_b32 s25, s26, 19
	s_add_i32 s0, s0, s25
	s_add_u32 s56, s92, s0
	s_addc_u32 s57, s93, 0
	s_add_u32 s56, s56, 0x34000000
	s_addc_u32 s57, s57, 0
	v_and_b32_e32 v251, 15, v246
	v_lshrrev_b32_e32 v252, 4, v246
	v_and_b32_e32 v253, 7, v251
	v_xor_b32_e32 v253, v253, v252
	v_lshlrev_b32_e32 v253, 4, v253
	v_lshl_add_u32 v242, v251, 7, v253
	v_xor_b32_e32 v243, 64, v242
	v_mov_b32_e32 v0, 0
	v_mov_b32_e32 v1, 0
	v_mov_b32_e32 v2, 0
	v_mov_b32_e32 v3, 0
	v_mov_b32_e32 v4, 0
	v_mov_b32_e32 v5, 0
	v_mov_b32_e32 v6, 0
	v_mov_b32_e32 v7, 0
	v_mov_b32_e32 v8, 0
	v_mov_b32_e32 v9, 0
	v_mov_b32_e32 v10, 0
	v_mov_b32_e32 v11, 0
	v_mov_b32_e32 v12, 0
	v_mov_b32_e32 v13, 0
	v_mov_b32_e32 v14, 0
	v_mov_b32_e32 v15, 0
	v_mov_b32_e32 v16, 0
	v_mov_b32_e32 v17, 0
	v_mov_b32_e32 v18, 0
	v_mov_b32_e32 v19, 0
	v_mov_b32_e32 v20, 0
	v_mov_b32_e32 v21, 0
	v_mov_b32_e32 v22, 0
	v_mov_b32_e32 v23, 0
	v_mov_b32_e32 v24, 0
	v_mov_b32_e32 v25, 0
	v_mov_b32_e32 v26, 0
	v_mov_b32_e32 v27, 0
	v_mov_b32_e32 v28, 0
	v_mov_b32_e32 v29, 0
	v_mov_b32_e32 v30, 0
	v_mov_b32_e32 v31, 0
	v_mov_b32_e32 v32, 0
	v_mov_b32_e32 v33, 0
	v_mov_b32_e32 v34, 0
	v_mov_b32_e32 v35, 0
	v_mov_b32_e32 v36, 0
	v_mov_b32_e32 v37, 0
	v_mov_b32_e32 v38, 0
	v_mov_b32_e32 v39, 0
	v_mov_b32_e32 v40, 0
	v_mov_b32_e32 v41, 0
	v_mov_b32_e32 v42, 0
	v_mov_b32_e32 v43, 0
	v_mov_b32_e32 v44, 0
	v_mov_b32_e32 v45, 0
	v_mov_b32_e32 v46, 0
	v_mov_b32_e32 v47, 0
	v_mov_b32_e32 v48, 0
	v_mov_b32_e32 v49, 0
	v_mov_b32_e32 v50, 0
	v_mov_b32_e32 v51, 0
	v_mov_b32_e32 v52, 0
	v_mov_b32_e32 v53, 0
	v_mov_b32_e32 v54, 0
	v_mov_b32_e32 v55, 0
	v_mov_b32_e32 v56, 0
	v_mov_b32_e32 v57, 0
	v_mov_b32_e32 v58, 0
	v_mov_b32_e32 v59, 0
	v_mov_b32_e32 v60, 0
	v_mov_b32_e32 v61, 0
	v_mov_b32_e32 v62, 0
	v_mov_b32_e32 v63, 0
	v_mov_b32_e32 v64, 0
	v_mov_b32_e32 v65, 0
	v_mov_b32_e32 v66, 0
	v_mov_b32_e32 v67, 0
	v_mov_b32_e32 v68, 0
	v_mov_b32_e32 v69, 0
	v_mov_b32_e32 v70, 0
	v_mov_b32_e32 v71, 0
	v_mov_b32_e32 v72, 0
	v_mov_b32_e32 v73, 0
	v_mov_b32_e32 v74, 0
	v_mov_b32_e32 v75, 0
	v_mov_b32_e32 v76, 0
	v_mov_b32_e32 v77, 0
	v_mov_b32_e32 v78, 0
	v_mov_b32_e32 v79, 0
	v_mov_b32_e32 v80, 0
	v_mov_b32_e32 v81, 0
	v_mov_b32_e32 v82, 0
	v_mov_b32_e32 v83, 0
	v_mov_b32_e32 v84, 0
	v_mov_b32_e32 v85, 0
	v_mov_b32_e32 v86, 0
	v_mov_b32_e32 v87, 0
	v_mov_b32_e32 v88, 0
	v_mov_b32_e32 v89, 0
	v_mov_b32_e32 v90, 0
	v_mov_b32_e32 v91, 0
	v_mov_b32_e32 v92, 0
	v_mov_b32_e32 v93, 0
	v_mov_b32_e32 v94, 0
	v_mov_b32_e32 v95, 0
	v_mov_b32_e32 v96, 0
	v_mov_b32_e32 v97, 0
	v_mov_b32_e32 v98, 0
	v_mov_b32_e32 v99, 0
	v_mov_b32_e32 v100, 0
	v_mov_b32_e32 v101, 0
	v_mov_b32_e32 v102, 0
	v_mov_b32_e32 v103, 0
	v_mov_b32_e32 v104, 0
	v_mov_b32_e32 v105, 0
	v_mov_b32_e32 v106, 0
	v_mov_b32_e32 v107, 0
	v_mov_b32_e32 v108, 0
	v_mov_b32_e32 v109, 0
	v_mov_b32_e32 v110, 0
	v_mov_b32_e32 v111, 0
	v_mov_b32_e32 v112, 0
	v_mov_b32_e32 v113, 0
	v_mov_b32_e32 v114, 0
	v_mov_b32_e32 v115, 0
	v_mov_b32_e32 v116, 0
	v_mov_b32_e32 v117, 0
	v_mov_b32_e32 v118, 0
	v_mov_b32_e32 v119, 0
	v_mov_b32_e32 v120, 0
	v_mov_b32_e32 v121, 0
	v_mov_b32_e32 v122, 0
	v_mov_b32_e32 v123, 0
	v_mov_b32_e32 v124, 0
	v_mov_b32_e32 v125, 0
	v_mov_b32_e32 v126, 0
	v_mov_b32_e32 v127, 0
	s_mov_b32 s25, 0
	s_mov_b32 s27, 0
	s_add_i32 m0, s27, s97
	s_nop 0
	global_load_lds_dwordx4 v234, s[28:29]
	s_add_i32 m0, m0, 0x400
	s_nop 0
	global_load_lds_dwordx4 v235, s[28:29]
	s_add_i32 m0, m0, 0x400
	s_nop 0
	global_load_lds_dwordx4 v236, s[28:29]
	s_add_i32 m0, m0, 0x400
	s_nop 0
	global_load_lds_dwordx4 v237, s[28:29]
	s_add_u32 s28, s28, 128
	s_addc_u32 s29, s29, 0
	global_load_dwordx4 v[128:131], v238, s[56:57]
	global_load_dwordx4 v[132:135], v239, s[56:57]
	global_load_dwordx4 v[136:139], v240, s[56:57]
	global_load_dwordx4 v[140:143], v241, s[56:57]
	s_cmp_lt_u32 s25, 31
	s_cselect_b32 s0, 1024, 0
	s_add_u32 s56, s56, s0
	s_addc_u32 s57, s57, 0
	s_add_i32 s25, s25, 1
	global_load_dwordx4 v[144:147], v238, s[56:57]
	global_load_dwordx4 v[148:151], v239, s[56:57]
	global_load_dwordx4 v[152:155], v240, s[56:57]
	global_load_dwordx4 v[156:159], v241, s[56:57]
	s_cmp_lt_u32 s25, 31
	s_cselect_b32 s0, 1024, 0
	s_add_u32 s56, s56, s0
	s_addc_u32 s57, s57, 0
	s_add_i32 s25, s25, 1
	s_movk_i32 s27, 0x4000
	s_add_i32 m0, s27, s97
	s_nop 0
	global_load_lds_dwordx4 v234, s[28:29]
	s_add_i32 m0, m0, 0x400
	s_nop 0
	global_load_lds_dwordx4 v235, s[28:29]
	s_add_i32 m0, m0, 0x400
	s_nop 0
	global_load_lds_dwordx4 v236, s[28:29]
	s_add_i32 m0, m0, 0x400
	s_nop 0
	global_load_lds_dwordx4 v237, s[28:29]
	s_add_u32 s28, s28, 128
	s_addc_u32 s29, s29, 0
	global_load_dwordx4 v[160:163], v238, s[56:57]
	global_load_dwordx4 v[164:167], v239, s[56:57]
	global_load_dwordx4 v[168:171], v240, s[56:57]
	global_load_dwordx4 v[172:175], v241, s[56:57]
	s_cmp_lt_u32 s25, 31
	s_cselect_b32 s0, 1024, 0
	s_add_u32 s56, s56, s0
	s_addc_u32 s57, s57, 0
	s_add_i32 s25, s25, 1
	s_mov_b32 s58, 0
	s_mov_b32 s59, 0
	s_mov_b32 s27, 0x8000
.Lg1_loop:
	s_waitcnt vmcnt(12)
	s_barrier
	global_load_dwordx4 v[176:179], v238, s[56:57]
	global_load_dwordx4 v[182:185], v239, s[56:57]
	global_load_dwordx4 v[186:189], v240, s[56:57]
	global_load_dwordx4 v[194:197], v241, s[56:57]
	s_cmp_lt_u32 s25, 31
	s_cselect_b32 s0, 1024, 0
	s_add_u32 s56, s56, s0
	s_addc_u32 s57, s57, 0
	s_add_i32 s25, s25, 1
	s_add_i32 m0, s27, s97
	s_nop 0
	global_load_lds_dwordx4 v234, s[28:29]
	s_add_i32 m0, m0, 0x400
	s_nop 0
	global_load_lds_dwordx4 v235, s[28:29]
	s_add_i32 m0, m0, 0x400
	s_nop 0
	global_load_lds_dwordx4 v236, s[28:29]
	s_add_i32 m0, m0, 0x400
	s_nop 0
	global_load_lds_dwordx4 v237, s[28:29]
	s_cmp_lt_u32 s58, 13
	s_cselect_b32 s0, 128, 0
	s_add_u32 s28, s28, s0
	s_addc_u32 s29, s29, 0
	v_add_u32_e32 v244, s59, v242
	v_add_u32_e32 v245, s59, v243
	ds_read_b128 v[198:201], v244 offset:0
	ds_read_b128 v[202:205], v244 offset:2048
	ds_read_b128 v[210:213], v244 offset:4096
	ds_read_b128 v[214:217], v244 offset:6144
	ds_read_b128 v[218:221], v244 offset:8192
	ds_read_b128 v[222:225], v244 offset:10240
	ds_read_b128 v[226:229], v244 offset:12288
	ds_read_b128 v[230:233], v244 offset:14336
	s_waitcnt lgkmcnt(4)
	v_mfma_f32_16x16x32_bf16 v[0:3], v[128:131], v[198:201], v[0:3]
	v_mfma_f32_16x16x32_bf16 v[32:35], v[132:135], v[198:201], v[32:35]
	v_mfma_f32_16x16x32_bf16 v[64:67], v[136:139], v[198:201], v[64:67]
	v_mfma_f32_16x16x32_bf16 v[96:99], v[140:143], v[198:201], v[96:99]
	v_mfma_f32_16x16x32_bf16 v[4:7], v[128:131], v[202:205], v[4:7]
	v_mfma_f32_16x16x32_bf16 v[36:39], v[132:135], v[202:205], v[36:39]
	v_mfma_f32_16x16x32_bf16 v[68:71], v[136:139], v[202:205], v[68:71]
	v_mfma_f32_16x16x32_bf16 v[100:103], v[140:143], v[202:205], v[100:103]
	v_mfma_f32_16x16x32_bf16 v[8:11], v[128:131], v[210:213], v[8:11]
	v_mfma_f32_16x16x32_bf16 v[40:43], v[132:135], v[210:213], v[40:43]
	v_mfma_f32_16x16x32_bf16 v[72:75], v[136:139], v[210:213], v[72:75]
	v_mfma_f32_16x16x32_bf16 v[104:107], v[140:143], v[210:213], v[104:107]
	v_mfma_f32_16x16x32_bf16 v[12:15], v[128:131], v[214:217], v[12:15]
	v_mfma_f32_16x16x32_bf16 v[44:47], v[132:135], v[214:217], v[44:47]
	v_mfma_f32_16x16x32_bf16 v[76:79], v[136:139], v[214:217], v[76:79]
	v_mfma_f32_16x16x32_bf16 v[108:111], v[140:143], v[214:217], v[108:111]
	s_waitcnt lgkmcnt(0)
	v_mfma_f32_16x16x32_bf16 v[16:19], v[128:131], v[218:221], v[16:19]
	v_mfma_f32_16x16x32_bf16 v[48:51], v[132:135], v[218:221], v[48:51]
	v_mfma_f32_16x16x32_bf16 v[80:83], v[136:139], v[218:221], v[80:83]
	v_mfma_f32_16x16x32_bf16 v[112:115], v[140:143], v[218:221], v[112:115]
	v_mfma_f32_16x16x32_bf16 v[20:23], v[128:131], v[222:225], v[20:23]
	v_mfma_f32_16x16x32_bf16 v[52:55], v[132:135], v[222:225], v[52:55]
	v_mfma_f32_16x16x32_bf16 v[84:87], v[136:139], v[222:225], v[84:87]
	v_mfma_f32_16x16x32_bf16 v[116:119], v[140:143], v[222:225], v[116:119]
	v_mfma_f32_16x16x32_bf16 v[24:27], v[128:131], v[226:229], v[24:27]
	v_mfma_f32_16x16x32_bf16 v[56:59], v[132:135], v[226:229], v[56:59]
	v_mfma_f32_16x16x32_bf16 v[88:91], v[136:139], v[226:229], v[88:91]
	v_mfma_f32_16x16x32_bf16 v[120:123], v[140:143], v[226:229], v[120:123]
	v_mfma_f32_16x16x32_bf16 v[28:31], v[128:131], v[230:233], v[28:31]
	v_mfma_f32_16x16x32_bf16 v[60:63], v[132:135], v[230:233], v[60:63]
	v_mfma_f32_16x16x32_bf16 v[92:95], v[136:139], v[230:233], v[92:95]
	v_mfma_f32_16x16x32_bf16 v[124:127], v[140:143], v[230:233], v[124:127]
	s_waitcnt vmcnt(16)
	global_load_dwordx4 v[128:131], v238, s[56:57]
	global_load_dwordx4 v[132:135], v239, s[56:57]
	global_load_dwordx4 v[136:139], v240, s[56:57]
	global_load_dwordx4 v[140:143], v241, s[56:57]
	s_cmp_lt_u32 s25, 31
	s_cselect_b32 s0, 1024, 0
	s_add_u32 s56, s56, s0
	s_addc_u32 s57, s57, 0
	s_add_i32 s25, s25, 1
	ds_read_b128 v[198:201], v245 offset:0
	ds_read_b128 v[202:205], v245 offset:2048
	ds_read_b128 v[210:213], v245 offset:4096
	ds_read_b128 v[214:217], v245 offset:6144
	ds_read_b128 v[218:221], v245 offset:8192
	ds_read_b128 v[222:225], v245 offset:10240
	ds_read_b128 v[226:229], v245 offset:12288
	ds_read_b128 v[230:233], v245 offset:14336
	s_waitcnt lgkmcnt(4)
	v_mfma_f32_16x16x32_bf16 v[0:3], v[144:147], v[198:201], v[0:3]
	v_mfma_f32_16x16x32_bf16 v[32:35], v[148:151], v[198:201], v[32:35]
	v_mfma_f32_16x16x32_bf16 v[64:67], v[152:155], v[198:201], v[64:67]
	v_mfma_f32_16x16x32_bf16 v[96:99], v[156:159], v[198:201], v[96:99]
	v_mfma_f32_16x16x32_bf16 v[4:7], v[144:147], v[202:205], v[4:7]
	v_mfma_f32_16x16x32_bf16 v[36:39], v[148:151], v[202:205], v[36:39]
	v_mfma_f32_16x16x32_bf16 v[68:71], v[152:155], v[202:205], v[68:71]
	v_mfma_f32_16x16x32_bf16 v[100:103], v[156:159], v[202:205], v[100:103]
	v_mfma_f32_16x16x32_bf16 v[8:11], v[144:147], v[210:213], v[8:11]
	v_mfma_f32_16x16x32_bf16 v[40:43], v[148:151], v[210:213], v[40:43]
	v_mfma_f32_16x16x32_bf16 v[72:75], v[152:155], v[210:213], v[72:75]
	v_mfma_f32_16x16x32_bf16 v[104:107], v[156:159], v[210:213], v[104:107]
	v_mfma_f32_16x16x32_bf16 v[12:15], v[144:147], v[214:217], v[12:15]
	v_mfma_f32_16x16x32_bf16 v[44:47], v[148:151], v[214:217], v[44:47]
	v_mfma_f32_16x16x32_bf16 v[76:79], v[152:155], v[214:217], v[76:79]
	v_mfma_f32_16x16x32_bf16 v[108:111], v[156:159], v[214:217], v[108:111]
	s_waitcnt lgkmcnt(0)
	v_mfma_f32_16x16x32_bf16 v[16:19], v[144:147], v[218:221], v[16:19]
	v_mfma_f32_16x16x32_bf16 v[48:51], v[148:151], v[218:221], v[48:51]
	v_mfma_f32_16x16x32_bf16 v[80:83], v[152:155], v[218:221], v[80:83]
	v_mfma_f32_16x16x32_bf16 v[112:115], v[156:159], v[218:221], v[112:115]
	v_mfma_f32_16x16x32_bf16 v[20:23], v[144:147], v[222:225], v[20:23]
	v_mfma_f32_16x16x32_bf16 v[52:55], v[148:151], v[222:225], v[52:55]
	v_mfma_f32_16x16x32_bf16 v[84:87], v[152:155], v[222:225], v[84:87]
	v_mfma_f32_16x16x32_bf16 v[116:119], v[156:159], v[222:225], v[116:119]
	v_mfma_f32_16x16x32_bf16 v[24:27], v[144:147], v[226:229], v[24:27]
	v_mfma_f32_16x16x32_bf16 v[56:59], v[148:151], v[226:229], v[56:59]
	v_mfma_f32_16x16x32_bf16 v[88:91], v[152:155], v[226:229], v[88:91]
	v_mfma_f32_16x16x32_bf16 v[120:123], v[156:159], v[226:229], v[120:123]
	v_mfma_f32_16x16x32_bf16 v[28:31], v[144:147], v[230:233], v[28:31]
	v_mfma_f32_16x16x32_bf16 v[60:63], v[148:151], v[230:233], v[60:63]
	v_mfma_f32_16x16x32_bf16 v[92:95], v[152:155], v[230:233], v[92:95]
	v_mfma_f32_16x16x32_bf16 v[124:127], v[156:159], v[230:233], v[124:127]
	s_add_i32 s59, s59, 0x4000
	s_cmp_lt_u32 s59, 0xc000
	s_cselect_b32 s59, s59, 0
	s_add_i32 s27, s27, 0x4000
	s_cmp_lt_u32 s27, 0xc000
	s_cselect_b32 s27, s27, 0
	s_add_i32 s58, s58, 1
	s_waitcnt vmcnt(12)
	s_barrier
	global_load_dwordx4 v[144:147], v238, s[56:57]
	global_load_dwordx4 v[148:151], v239, s[56:57]
	global_load_dwordx4 v[152:155], v240, s[56:57]
	global_load_dwordx4 v[156:159], v241, s[56:57]
	s_cmp_lt_u32 s25, 31
	s_cselect_b32 s0, 1024, 0
	s_add_u32 s56, s56, s0
	s_addc_u32 s57, s57, 0
	s_add_i32 s25, s25, 1
	s_add_i32 m0, s27, s97
	s_nop 0
	global_load_lds_dwordx4 v234, s[28:29]
	s_add_i32 m0, m0, 0x400
	s_nop 0
	global_load_lds_dwordx4 v235, s[28:29]
	s_add_i32 m0, m0, 0x400
	s_nop 0
	global_load_lds_dwordx4 v236, s[28:29]
	s_add_i32 m0, m0, 0x400
	s_nop 0
	global_load_lds_dwordx4 v237, s[28:29]
	s_cmp_lt_u32 s58, 13
	s_cselect_b32 s0, 128, 0
	s_add_u32 s28, s28, s0
	s_addc_u32 s29, s29, 0
	v_add_u32_e32 v244, s59, v242
	v_add_u32_e32 v245, s59, v243
	ds_read_b128 v[198:201], v244 offset:0
	ds_read_b128 v[202:205], v244 offset:2048
	ds_read_b128 v[210:213], v244 offset:4096
	ds_read_b128 v[214:217], v244 offset:6144
	ds_read_b128 v[218:221], v244 offset:8192
	ds_read_b128 v[222:225], v244 offset:10240
	ds_read_b128 v[226:229], v244 offset:12288
	ds_read_b128 v[230:233], v244 offset:14336
	s_waitcnt lgkmcnt(4)
	v_mfma_f32_16x16x32_bf16 v[0:3], v[160:163], v[198:201], v[0:3]
	v_mfma_f32_16x16x32_bf16 v[32:35], v[164:167], v[198:201], v[32:35]
	v_mfma_f32_16x16x32_bf16 v[64:67], v[168:171], v[198:201], v[64:67]
	v_mfma_f32_16x16x32_bf16 v[96:99], v[172:175], v[198:201], v[96:99]
	v_mfma_f32_16x16x32_bf16 v[4:7], v[160:163], v[202:205], v[4:7]
	v_mfma_f32_16x16x32_bf16 v[36:39], v[164:167], v[202:205], v[36:39]
	v_mfma_f32_16x16x32_bf16 v[68:71], v[168:171], v[202:205], v[68:71]
	v_mfma_f32_16x16x32_bf16 v[100:103], v[172:175], v[202:205], v[100:103]
	v_mfma_f32_16x16x32_bf16 v[8:11], v[160:163], v[210:213], v[8:11]
	v_mfma_f32_16x16x32_bf16 v[40:43], v[164:167], v[210:213], v[40:43]
	v_mfma_f32_16x16x32_bf16 v[72:75], v[168:171], v[210:213], v[72:75]
	v_mfma_f32_16x16x32_bf16 v[104:107], v[172:175], v[210:213], v[104:107]
	v_mfma_f32_16x16x32_bf16 v[12:15], v[160:163], v[214:217], v[12:15]
	v_mfma_f32_16x16x32_bf16 v[44:47], v[164:167], v[214:217], v[44:47]
	v_mfma_f32_16x16x32_bf16 v[76:79], v[168:171], v[214:217], v[76:79]
	v_mfma_f32_16x16x32_bf16 v[108:111], v[172:175], v[214:217], v[108:111]
	s_waitcnt lgkmcnt(0)
	v_mfma_f32_16x16x32_bf16 v[16:19], v[160:163], v[218:221], v[16:19]
	v_mfma_f32_16x16x32_bf16 v[48:51], v[164:167], v[218:221], v[48:51]
	v_mfma_f32_16x16x32_bf16 v[80:83], v[168:171], v[218:221], v[80:83]
	v_mfma_f32_16x16x32_bf16 v[112:115], v[172:175], v[218:221], v[112:115]
	v_mfma_f32_16x16x32_bf16 v[20:23], v[160:163], v[222:225], v[20:23]
	v_mfma_f32_16x16x32_bf16 v[52:55], v[164:167], v[222:225], v[52:55]
	v_mfma_f32_16x16x32_bf16 v[84:87], v[168:171], v[222:225], v[84:87]
	v_mfma_f32_16x16x32_bf16 v[116:119], v[172:175], v[222:225], v[116:119]
	v_mfma_f32_16x16x32_bf16 v[24:27], v[160:163], v[226:229], v[24:27]
	v_mfma_f32_16x16x32_bf16 v[56:59], v[164:167], v[226:229], v[56:59]
	v_mfma_f32_16x16x32_bf16 v[88:91], v[168:171], v[226:229], v[88:91]
	v_mfma_f32_16x16x32_bf16 v[120:123], v[172:175], v[226:229], v[120:123]
	v_mfma_f32_16x16x32_bf16 v[28:31], v[160:163], v[230:233], v[28:31]
	v_mfma_f32_16x16x32_bf16 v[60:63], v[164:167], v[230:233], v[60:63]
	v_mfma_f32_16x16x32_bf16 v[92:95], v[168:171], v[230:233], v[92:95]
	v_mfma_f32_16x16x32_bf16 v[124:127], v[172:175], v[230:233], v[124:127]
	s_waitcnt vmcnt(16)
	global_load_dwordx4 v[160:163], v238, s[56:57]
	global_load_dwordx4 v[164:167], v239, s[56:57]
	global_load_dwordx4 v[168:171], v240, s[56:57]
	global_load_dwordx4 v[172:175], v241, s[56:57]
	s_cmp_lt_u32 s25, 31
	s_cselect_b32 s0, 1024, 0
	s_add_u32 s56, s56, s0
	s_addc_u32 s57, s57, 0
	s_add_i32 s25, s25, 1
	ds_read_b128 v[198:201], v245 offset:0
	ds_read_b128 v[202:205], v245 offset:2048
	ds_read_b128 v[210:213], v245 offset:4096
	ds_read_b128 v[214:217], v245 offset:6144
	ds_read_b128 v[218:221], v245 offset:8192
	ds_read_b128 v[222:225], v245 offset:10240
	ds_read_b128 v[226:229], v245 offset:12288
	ds_read_b128 v[230:233], v245 offset:14336
	s_waitcnt lgkmcnt(4)
	v_mfma_f32_16x16x32_bf16 v[0:3], v[176:179], v[198:201], v[0:3]
	v_mfma_f32_16x16x32_bf16 v[32:35], v[182:185], v[198:201], v[32:35]
	v_mfma_f32_16x16x32_bf16 v[64:67], v[186:189], v[198:201], v[64:67]
	v_mfma_f32_16x16x32_bf16 v[96:99], v[194:197], v[198:201], v[96:99]
	v_mfma_f32_16x16x32_bf16 v[4:7], v[176:179], v[202:205], v[4:7]
	v_mfma_f32_16x16x32_bf16 v[36:39], v[182:185], v[202:205], v[36:39]
	v_mfma_f32_16x16x32_bf16 v[68:71], v[186:189], v[202:205], v[68:71]
	v_mfma_f32_16x16x32_bf16 v[100:103], v[194:197], v[202:205], v[100:103]
	v_mfma_f32_16x16x32_bf16 v[8:11], v[176:179], v[210:213], v[8:11]
	v_mfma_f32_16x16x32_bf16 v[40:43], v[182:185], v[210:213], v[40:43]
	v_mfma_f32_16x16x32_bf16 v[72:75], v[186:189], v[210:213], v[72:75]
	v_mfma_f32_16x16x32_bf16 v[104:107], v[194:197], v[210:213], v[104:107]
	v_mfma_f32_16x16x32_bf16 v[12:15], v[176:179], v[214:217], v[12:15]
	v_mfma_f32_16x16x32_bf16 v[44:47], v[182:185], v[214:217], v[44:47]
	v_mfma_f32_16x16x32_bf16 v[76:79], v[186:189], v[214:217], v[76:79]
	v_mfma_f32_16x16x32_bf16 v[108:111], v[194:197], v[214:217], v[108:111]
	s_waitcnt lgkmcnt(0)
	v_mfma_f32_16x16x32_bf16 v[16:19], v[176:179], v[218:221], v[16:19]
	v_mfma_f32_16x16x32_bf16 v[48:51], v[182:185], v[218:221], v[48:51]
	v_mfma_f32_16x16x32_bf16 v[80:83], v[186:189], v[218:221], v[80:83]
	v_mfma_f32_16x16x32_bf16 v[112:115], v[194:197], v[218:221], v[112:115]
	v_mfma_f32_16x16x32_bf16 v[20:23], v[176:179], v[222:225], v[20:23]
	v_mfma_f32_16x16x32_bf16 v[52:55], v[182:185], v[222:225], v[52:55]
	v_mfma_f32_16x16x32_bf16 v[84:87], v[186:189], v[222:225], v[84:87]
	v_mfma_f32_16x16x32_bf16 v[116:119], v[194:197], v[222:225], v[116:119]
	v_mfma_f32_16x16x32_bf16 v[24:27], v[176:179], v[226:229], v[24:27]
	v_mfma_f32_16x16x32_bf16 v[56:59], v[182:185], v[226:229], v[56:59]
	v_mfma_f32_16x16x32_bf16 v[88:91], v[186:189], v[226:229], v[88:91]
	v_mfma_f32_16x16x32_bf16 v[120:123], v[194:197], v[226:229], v[120:123]
	v_mfma_f32_16x16x32_bf16 v[28:31], v[176:179], v[230:233], v[28:31]
	v_mfma_f32_16x16x32_bf16 v[60:63], v[182:185], v[230:233], v[60:63]
	v_mfma_f32_16x16x32_bf16 v[92:95], v[186:189], v[230:233], v[92:95]
	v_mfma_f32_16x16x32_bf16 v[124:127], v[194:197], v[230:233], v[124:127]
	s_add_i32 s59, s59, 0x4000
	s_cmp_lt_u32 s59, 0xc000
	s_cselect_b32 s59, s59, 0
	s_add_i32 s27, s27, 0x4000
	s_cmp_lt_u32 s27, 0xc000
	s_cselect_b32 s27, s27, 0
	s_add_i32 s58, s58, 1
	s_cmp_lt_u32 s58, 16
	s_cbranch_scc1 .Lg1_loop
	s_waitcnt vmcnt(0)
	s_barrier
	s_nop 7
	s_nop 7
	s_lshl_b32 s0, s24, 9
	s_add_u32 s28, s92, s0
	s_addc_u32 s29, s93, 0
	s_add_u32 s28, s28, 0x36b00000
	s_addc_u32 s29, s29, 0
	v_lshlrev_b32_e32 v244, 2, v251
	global_load_dword v128, v244, s[28:29] offset:0
	global_load_dword v129, v244, s[28:29] offset:64
	global_load_dword v130, v244, s[28:29] offset:128
	global_load_dword v131, v244, s[28:29] offset:192
	global_load_dword v132, v244, s[28:29] offset:256
	global_load_dword v133, v244, s[28:29] offset:320
	global_load_dword v134, v244, s[28:29] offset:384
	global_load_dword v135, v244, s[28:29] offset:448
	s_mul_i32 s0, s24, 0xb0000
	s_lshl_b32 s25, s26, 9
	s_add_i32 s0, s0, s25
	s_add_u32 s28, s92, s0
	s_addc_u32 s29, s93, 0
	s_add_u32 s28, s28, 0x8000000
	s_addc_u32 s29, s29, 0
	v_mul_u32_u24_e32 v245, 0x1600, v251
	v_lshl_add_u32 v245, v247, 7, v245
	v_lshl_add_u32 v245, v252, 3, v245
	s_waitcnt vmcnt(0)
	v_mul_f32_e32 v0, v128, v0
	v_mul_f32_e32 v1, v128, v1
	v_mul_f32_e32 v2, v128, v2
	v_mul_f32_e32 v3, v128, v3
	v_cvt_pk_bf16_f32 v246, v0, v1
	v_cvt_pk_bf16_f32 v247, v2, v3
	global_store_dwordx2 v245, v[246:247], s[28:29] offset:0
	v_mul_f32_e32 v32, v128, v32
	v_mul_f32_e32 v33, v128, v33
	v_mul_f32_e32 v34, v128, v34
	v_mul_f32_e32 v35, v128, v35
	v_cvt_pk_bf16_f32 v248, v32, v33
	v_cvt_pk_bf16_f32 v249, v34, v35
	global_store_dwordx2 v245, v[248:249], s[28:29] offset:32
	v_mul_f32_e32 v64, v128, v64
	v_mul_f32_e32 v65, v128, v65
	v_mul_f32_e32 v66, v128, v66
	v_mul_f32_e32 v67, v128, v67
	v_cvt_pk_bf16_f32 v250, v64, v65
	v_cvt_pk_bf16_f32 v251, v66, v67
	global_store_dwordx2 v245, v[250:251], s[28:29] offset:64
	v_mul_f32_e32 v96, v128, v96
	v_mul_f32_e32 v97, v128, v97
	v_mul_f32_e32 v98, v128, v98
	v_mul_f32_e32 v99, v128, v99
	v_cvt_pk_bf16_f32 v252, v96, v97
	v_cvt_pk_bf16_f32 v253, v98, v99
	global_store_dwordx2 v245, v[252:253], s[28:29] offset:96
	v_add_u32_e32 v245, 0x16000, v245
	v_mul_f32_e32 v4, v129, v4
	v_mul_f32_e32 v5, v129, v5
	v_mul_f32_e32 v6, v129, v6
	v_mul_f32_e32 v7, v129, v7
	v_cvt_pk_bf16_f32 v246, v4, v5
	v_cvt_pk_bf16_f32 v247, v6, v7
	global_store_dwordx2 v245, v[246:247], s[28:29] offset:0
	v_mul_f32_e32 v36, v129, v36
	v_mul_f32_e32 v37, v129, v37
	v_mul_f32_e32 v38, v129, v38
	v_mul_f32_e32 v39, v129, v39
	v_cvt_pk_bf16_f32 v248, v36, v37
	v_cvt_pk_bf16_f32 v249, v38, v39
	global_store_dwordx2 v245, v[248:249], s[28:29] offset:32
	v_mul_f32_e32 v68, v129, v68
	v_mul_f32_e32 v69, v129, v69
	v_mul_f32_e32 v70, v129, v70
	v_mul_f32_e32 v71, v129, v71
	v_cvt_pk_bf16_f32 v250, v68, v69
	v_cvt_pk_bf16_f32 v251, v70, v71
	global_store_dwordx2 v245, v[250:251], s[28:29] offset:64
	v_mul_f32_e32 v100, v129, v100
	v_mul_f32_e32 v101, v129, v101
	v_mul_f32_e32 v102, v129, v102
	v_mul_f32_e32 v103, v129, v103
	v_cvt_pk_bf16_f32 v252, v100, v101
	v_cvt_pk_bf16_f32 v253, v102, v103
	global_store_dwordx2 v245, v[252:253], s[28:29] offset:96
	v_add_u32_e32 v245, 0x16000, v245
	v_mul_f32_e32 v8, v130, v8
	v_mul_f32_e32 v9, v130, v9
	v_mul_f32_e32 v10, v130, v10
	v_mul_f32_e32 v11, v130, v11
	v_cvt_pk_bf16_f32 v246, v8, v9
	v_cvt_pk_bf16_f32 v247, v10, v11
	global_store_dwordx2 v245, v[246:247], s[28:29] offset:0
	v_mul_f32_e32 v40, v130, v40
	v_mul_f32_e32 v41, v130, v41
	v_mul_f32_e32 v42, v130, v42
	v_mul_f32_e32 v43, v130, v43
	v_cvt_pk_bf16_f32 v248, v40, v41
	v_cvt_pk_bf16_f32 v249, v42, v43
	global_store_dwordx2 v245, v[248:249], s[28:29] offset:32
	v_mul_f32_e32 v72, v130, v72
	v_mul_f32_e32 v73, v130, v73
	v_mul_f32_e32 v74, v130, v74
	v_mul_f32_e32 v75, v130, v75
	v_cvt_pk_bf16_f32 v250, v72, v73
	v_cvt_pk_bf16_f32 v251, v74, v75
	global_store_dwordx2 v245, v[250:251], s[28:29] offset:64
	v_mul_f32_e32 v104, v130, v104
	v_mul_f32_e32 v105, v130, v105
	v_mul_f32_e32 v106, v130, v106
	v_mul_f32_e32 v107, v130, v107
	v_cvt_pk_bf16_f32 v252, v104, v105
	v_cvt_pk_bf16_f32 v253, v106, v107
	global_store_dwordx2 v245, v[252:253], s[28:29] offset:96
	v_add_u32_e32 v245, 0x16000, v245
	v_mul_f32_e32 v12, v131, v12
	v_mul_f32_e32 v13, v131, v13
	v_mul_f32_e32 v14, v131, v14
	v_mul_f32_e32 v15, v131, v15
	v_cvt_pk_bf16_f32 v246, v12, v13
	v_cvt_pk_bf16_f32 v247, v14, v15
	global_store_dwordx2 v245, v[246:247], s[28:29] offset:0
	v_mul_f32_e32 v44, v131, v44
	v_mul_f32_e32 v45, v131, v45
	v_mul_f32_e32 v46, v131, v46
	v_mul_f32_e32 v47, v131, v47
	v_cvt_pk_bf16_f32 v248, v44, v45
	v_cvt_pk_bf16_f32 v249, v46, v47
	global_store_dwordx2 v245, v[248:249], s[28:29] offset:32
	v_mul_f32_e32 v76, v131, v76
	v_mul_f32_e32 v77, v131, v77
	v_mul_f32_e32 v78, v131, v78
	v_mul_f32_e32 v79, v131, v79
	v_cvt_pk_bf16_f32 v250, v76, v77
	v_cvt_pk_bf16_f32 v251, v78, v79
	global_store_dwordx2 v245, v[250:251], s[28:29] offset:64
	v_mul_f32_e32 v108, v131, v108
	v_mul_f32_e32 v109, v131, v109
	v_mul_f32_e32 v110, v131, v110
	v_mul_f32_e32 v111, v131, v111
	v_cvt_pk_bf16_f32 v252, v108, v109
	v_cvt_pk_bf16_f32 v253, v110, v111
	global_store_dwordx2 v245, v[252:253], s[28:29] offset:96
	v_add_u32_e32 v245, 0x16000, v245
	v_mul_f32_e32 v16, v132, v16
	v_mul_f32_e32 v17, v132, v17
	v_mul_f32_e32 v18, v132, v18
	v_mul_f32_e32 v19, v132, v19
	v_cvt_pk_bf16_f32 v246, v16, v17
	v_cvt_pk_bf16_f32 v247, v18, v19
	global_store_dwordx2 v245, v[246:247], s[28:29] offset:0
	v_mul_f32_e32 v48, v132, v48
	v_mul_f32_e32 v49, v132, v49
	v_mul_f32_e32 v50, v132, v50
	v_mul_f32_e32 v51, v132, v51
	v_cvt_pk_bf16_f32 v248, v48, v49
	v_cvt_pk_bf16_f32 v249, v50, v51
	global_store_dwordx2 v245, v[248:249], s[28:29] offset:32
	v_mul_f32_e32 v80, v132, v80
	v_mul_f32_e32 v81, v132, v81
	v_mul_f32_e32 v82, v132, v82
	v_mul_f32_e32 v83, v132, v83
	v_cvt_pk_bf16_f32 v250, v80, v81
	v_cvt_pk_bf16_f32 v251, v82, v83
	global_store_dwordx2 v245, v[250:251], s[28:29] offset:64
	v_mul_f32_e32 v112, v132, v112
	v_mul_f32_e32 v113, v132, v113
	v_mul_f32_e32 v114, v132, v114
	v_mul_f32_e32 v115, v132, v115
	v_cvt_pk_bf16_f32 v252, v112, v113
	v_cvt_pk_bf16_f32 v253, v114, v115
	global_store_dwordx2 v245, v[252:253], s[28:29] offset:96
	v_add_u32_e32 v245, 0x16000, v245
	v_mul_f32_e32 v20, v133, v20
	v_mul_f32_e32 v21, v133, v21
	v_mul_f32_e32 v22, v133, v22
	v_mul_f32_e32 v23, v133, v23
	v_cvt_pk_bf16_f32 v246, v20, v21
	v_cvt_pk_bf16_f32 v247, v22, v23
	global_store_dwordx2 v245, v[246:247], s[28:29] offset:0
	v_mul_f32_e32 v52, v133, v52
	v_mul_f32_e32 v53, v133, v53
	v_mul_f32_e32 v54, v133, v54
	v_mul_f32_e32 v55, v133, v55
	v_cvt_pk_bf16_f32 v248, v52, v53
	v_cvt_pk_bf16_f32 v249, v54, v55
	global_store_dwordx2 v245, v[248:249], s[28:29] offset:32
	v_mul_f32_e32 v84, v133, v84
	v_mul_f32_e32 v85, v133, v85
	v_mul_f32_e32 v86, v133, v86
	v_mul_f32_e32 v87, v133, v87
	v_cvt_pk_bf16_f32 v250, v84, v85
	v_cvt_pk_bf16_f32 v251, v86, v87
	global_store_dwordx2 v245, v[250:251], s[28:29] offset:64
	v_mul_f32_e32 v116, v133, v116
	v_mul_f32_e32 v117, v133, v117
	v_mul_f32_e32 v118, v133, v118
	v_mul_f32_e32 v119, v133, v119
	v_cvt_pk_bf16_f32 v252, v116, v117
	v_cvt_pk_bf16_f32 v253, v118, v119
	global_store_dwordx2 v245, v[252:253], s[28:29] offset:96
	v_add_u32_e32 v245, 0x16000, v245
	v_mul_f32_e32 v24, v134, v24
	v_mul_f32_e32 v25, v134, v25
	v_mul_f32_e32 v26, v134, v26
	v_mul_f32_e32 v27, v134, v27
	v_cvt_pk_bf16_f32 v246, v24, v25
	v_cvt_pk_bf16_f32 v247, v26, v27
	global_store_dwordx2 v245, v[246:247], s[28:29] offset:0
	v_mul_f32_e32 v56, v134, v56
	v_mul_f32_e32 v57, v134, v57
	v_mul_f32_e32 v58, v134, v58
	v_mul_f32_e32 v59, v134, v59
	v_cvt_pk_bf16_f32 v248, v56, v57
	v_cvt_pk_bf16_f32 v249, v58, v59
	global_store_dwordx2 v245, v[248:249], s[28:29] offset:32
	v_mul_f32_e32 v88, v134, v88
	v_mul_f32_e32 v89, v134, v89
	v_mul_f32_e32 v90, v134, v90
	v_mul_f32_e32 v91, v134, v91
	v_cvt_pk_bf16_f32 v250, v88, v89
	v_cvt_pk_bf16_f32 v251, v90, v91
	global_store_dwordx2 v245, v[250:251], s[28:29] offset:64
	v_mul_f32_e32 v120, v134, v120
	v_mul_f32_e32 v121, v134, v121
	v_mul_f32_e32 v122, v134, v122
	v_mul_f32_e32 v123, v134, v123
	v_cvt_pk_bf16_f32 v252, v120, v121
	v_cvt_pk_bf16_f32 v253, v122, v123
	global_store_dwordx2 v245, v[252:253], s[28:29] offset:96
	v_add_u32_e32 v245, 0x16000, v245
	v_mul_f32_e32 v28, v135, v28
	v_mul_f32_e32 v29, v135, v29
	v_mul_f32_e32 v30, v135, v30
	v_mul_f32_e32 v31, v135, v31
	v_cvt_pk_bf16_f32 v246, v28, v29
	v_cvt_pk_bf16_f32 v247, v30, v31
	global_store_dwordx2 v245, v[246:247], s[28:29] offset:0
	v_mul_f32_e32 v60, v135, v60
	v_mul_f32_e32 v61, v135, v61
	v_mul_f32_e32 v62, v135, v62
	v_mul_f32_e32 v63, v135, v63
	v_cvt_pk_bf16_f32 v248, v60, v61
	v_cvt_pk_bf16_f32 v249, v62, v63
	global_store_dwordx2 v245, v[248:249], s[28:29] offset:32
	v_mul_f32_e32 v92, v135, v92
	v_mul_f32_e32 v93, v135, v93
	v_mul_f32_e32 v94, v135, v94
	v_mul_f32_e32 v95, v135, v95
	v_cvt_pk_bf16_f32 v250, v92, v93
	v_cvt_pk_bf16_f32 v251, v94, v95
	global_store_dwordx2 v245, v[250:251], s[28:29] offset:64
	v_mul_f32_e32 v124, v135, v124
	v_mul_f32_e32 v125, v135, v125
	v_mul_f32_e32 v126, v135, v126
	v_mul_f32_e32 v127, v135, v127
	v_cvt_pk_bf16_f32 v252, v124, v125
	v_cvt_pk_bf16_f32 v253, v126, v127
	global_store_dwordx2 v245, v[252:253], s[28:29] offset:96

	s_add_i32 s30, s30, s36
	s_cmp_lt_i32 s30, s31
	s_cbranch_scc1 .LBB0_154
